# v13 + attention wave groups staggered by half a step (waves 4-7 lag one phase, 2 barriers per step, no setprio in PV)
# baseline (speedup 1.0000x reference)
.LBB0_1038:
	s_or_b64 exec, exec, s[4:5]
	v_and_b32_e32 v0, 0x60, v26
	s_movk_i32 s4, 0x90
	v_lshlrev_b32_e32 v2, 3, v32
	v_mad_u32_u24 v207, v203, s4, 0
	v_mad_u64_u32 v[0:1], s[4:5], v28, s4, v[0:1]
	v_and_or_b32 v0, v2, 8, v0
	v_lshlrev_b32_e32 v1, 6, v203
	v_add_u32_e32 v208, 0, v0
	v_add3_u32 v204, v207, v1, v184
	v_add_u32_e32 v1, 0, v4
	v_add_u32_e32 v205, 0x9800, v208
	s_waitcnt vmcnt(3)
	ds_write_b128 v1, v[8:11] offset:13312
	s_waitcnt vmcnt(2)
	ds_write2_b64 v205, v[16:17], v[18:19] offset0:128 offset1:130
	s_waitcnt lgkmcnt(0)
	s_barrier
	ds_read_b128 v[0:3], v204
	ds_read_b128 v[4:7], v204 offset:32
	ds_read_b128 v[8:11], v204 offset:6656
	ds_read_b128 v[12:15], v204 offset:6688
	ds_read_b128 v[16:19], v204 offset:64
	ds_read_b128 v[28:31], v204 offset:96
	ds_read_b128 v[64:67], v204 offset:6720
	ds_read_b128 v[68:71], v204 offset:6752
	ds_read_b128 v[72:75], v204 offset:128
	ds_read_b128 v[76:79], v204 offset:160
	ds_read_b128 v[80:83], v204 offset:6784
	ds_read_b128 v[84:87], v204 offset:6816
	s_mov_b32 s91, 2
	s_lshl_b32 s87, s6, 2
	s_waitcnt lgkmcnt(11)
	v_mfma_f32_32x32x16_bf16 v[48:63], v[0:3], v[100:103], 0
	s_mov_b32 s79, 0
	s_waitcnt lgkmcnt(9)
	v_mfma_f32_32x32x16_bf16 v[32:47], v[8:11], v[100:103], 0
	v_mfma_f32_32x32x16_bf16 v[48:63], v[4:7], v[104:107], v[48:63]
	s_waitcnt lgkmcnt(8)
	v_mfma_f32_32x32x16_bf16 v[32:47], v[12:15], v[104:107], v[32:47]
	s_waitcnt lgkmcnt(7)
	v_mfma_f32_32x32x16_bf16 v[48:63], v[16:19], v[108:111], v[48:63]
	s_waitcnt lgkmcnt(5)
	v_mfma_f32_32x32x16_bf16 v[32:47], v[64:67], v[108:111], v[32:47]
	v_mfma_f32_32x32x16_bf16 v[48:63], v[28:31], v[112:115], v[48:63]
	s_waitcnt lgkmcnt(4)
	v_mfma_f32_32x32x16_bf16 v[32:47], v[68:71], v[112:115], v[32:47]
	s_waitcnt lgkmcnt(3)
	v_mfma_f32_32x32x16_bf16 v[48:63], v[72:75], v[116:119], v[48:63]
	s_waitcnt lgkmcnt(1)
	v_mfma_f32_32x32x16_bf16 v[32:47], v[80:83], v[116:119], v[32:47]
	v_mfma_f32_32x32x16_bf16 v[48:63], v[76:79], v[120:123], v[48:63]
	s_waitcnt lgkmcnt(0)
	v_mfma_f32_32x32x16_bf16 v[32:47], v[84:87], v[120:123], v[32:47]
	ds_read_b128 v[172:175], v204 offset:13312
	ds_read_b128 v[152:155], v204 offset:13344
	ds_read_b128 v[180:183], v204 offset:19968
	ds_read_b128 v[164:167], v204 offset:20000
	ds_read_b128 v[156:159], v204 offset:13376
	ds_read_b128 v[140:143], v204 offset:13408
	ds_read_b128 v[176:179], v204 offset:20032
	ds_read_b128 v[160:163], v204 offset:20064
	ds_read_b128 v[148:151], v204 offset:13440
	ds_read_b128 v[136:139], v204 offset:13472
	ds_read_b128 v[168:171], v204 offset:20096
	ds_read_b128 v[144:147], v204 offset:20128
	s_add_u32 s4, s60, 0x100
	v_lshl_add_u64 v[0:1], s[60:61], 0, v[24:25]
	v_mov_b32_e32 v27, v97
	s_addc_u32 s5, 0, 0
	v_lshl_add_u64 v[190:191], v[0:1], 0, v[26:27]
	v_lshl_add_u64 v[0:1], s[4:5], 0, v[24:25]
	v_mov_b32_e32 v199, 0
	v_lshl_add_u64 v[188:189], s[96:97], 0, v[20:21]
	v_lshl_add_u64 v[186:187], s[96:97], 0, v[22:23]
	v_lshl_add_u64 v[98:99], v[0:1], 0, v[26:27]
	s_add_u32 s98, s94, 0x12209000
	s_addc_u32 s99, s95, 0
	s_add_u32 s100, s94, 0x11200000
	s_addc_u32 s101, s95, 0

	s_movk_i32 s93, 0xbf
	v_mov_b32_e32 v0, 0
	v_mov_b32_e32 v1, v199
	v_mov_b32_e32 v2, v199
	v_mov_b32_e32 v3, v199
	v_mov_b32_e32 v4, v199
	v_mov_b32_e32 v5, v199
	v_mov_b32_e32 v6, v199
	v_mov_b32_e32 v7, v199
	v_mov_b32_e32 v8, v199
	v_mov_b32_e32 v9, v199
	v_mov_b32_e32 v10, v199
	v_mov_b32_e32 v11, v199
	v_mov_b32_e32 v12, v199
	v_mov_b32_e32 v13, v199
	v_mov_b32_e32 v14, v199
	v_mov_b32_e32 v15, v199
	v_mov_b32_e32 v16, 0
	v_mov_b32_e32 v17, v199
	v_mov_b32_e32 v18, v199
	v_mov_b32_e32 v19, v199
	v_mov_b32_e32 v20, v199
	v_mov_b32_e32 v21, v199
	v_mov_b32_e32 v22, v199
	v_mov_b32_e32 v23, v199
	v_mov_b32_e32 v24, v199
	v_mov_b32_e32 v25, v199
	v_mov_b32_e32 v26, v199
	v_mov_b32_e32 v27, v199
	v_mov_b32_e32 v28, v199
	v_mov_b32_e32 v29, v199
	v_mov_b32_e32 v30, v199
	v_mov_b32_e32 v31, v199
	s_getreg_b32 s4, hwreg(HW_REG_HW_ID, 0, 6)
	s_and_b32 s4, s4, 63
	s_lshl_b32 s4, s4, 2
	s_add_i32 s4, s4, 0x20840
	v_mov_b32_e32 v253, s4
	ds_read_b32 v253, v253
	s_waitcnt lgkmcnt(0)
	v_readfirstlane_b32 s4, v253
	s_cmp_ge_u32 s4, 4
	s_cbranch_scc1 .Lst7A_Lentry


.Lat7A_A_h0:
	s_or_b64 exec, exec, s[4:5]
	global_load_dwordx4 v[132:135], v[200:201], off offset:256

	s_waitcnt lgkmcnt(7)
	v_mfma_f32_32x32x16_bf16 v[80:95], v[176:179], v[108:111], v[80:95]
	v_exp_f32_e32 v32, v32
	v_exp_f32_e32 v33, v33
	v_exp_f32_e32 v34, v34
	v_add_f32_e32 v251, v32, v33
	v_cvt_pk_bf16_f32 v48, v48, v49
	v_exp_f32_e32 v35, v35
	v_mfma_f32_32x32x16_bf16 v[64:79], v[140:143], v[112:115], v[64:79]
	v_add_f32_e32 v251, v34, v251
	v_exp_f32_e32 v36, v36
	v_add_f32_e32 v251, v35, v251
	v_cvt_pk_bf16_f32 v49, v50, v51
	v_exp_f32_e32 v37, v37
	v_add_f32_e32 v251, v36, v251
	s_waitcnt lgkmcnt(6)
	v_mfma_f32_32x32x16_bf16 v[80:95], v[160:163], v[112:115], v[80:95]
	v_exp_f32_e32 v38, v38
	v_add_f32_e32 v251, v37, v251
	v_cvt_pk_bf16_f32 v50, v52, v53
	v_exp_f32_e32 v39, v39
	v_add_f32_e32 v251, v38, v251
	v_exp_f32_e32 v40, v40
	v_add_f32_e32 v251, v39, v251
	s_waitcnt lgkmcnt(5)
	v_mfma_f32_32x32x16_bf16 v[64:79], v[148:151], v[116:119], v[64:79]
	v_cvt_pk_bf16_f32 v51, v54, v55
	v_exp_f32_e32 v41, v41
	v_add_f32_e32 v251, v40, v251
	v_exp_f32_e32 v42, v42
	v_add_f32_e32 v251, v41, v251
	v_cvt_pk_bf16_f32 v52, v56, v57
	v_exp_f32_e32 v43, v43
	v_add_u32_e32 v198, v207, v184
	ds_read_b128 v[210:213], v198 offset:44544
	ds_read_b128 v[214:217], v198 offset:39936
	ds_read_b128 v[218:221], v198 offset:39968
	ds_read_b128 v[222:225], v198 offset:44576
	ds_read_b128 v[226:229], v198 offset:40000
	ds_read_b128 v[230:233], v198 offset:44608
	ds_read_b128 v[234:237], v198 offset:40032
	ds_read_b128 v[238:241], v198 offset:44640
	s_waitcnt lgkmcnt(11)
	v_mfma_f32_32x32x16_bf16 v[80:95], v[168:171], v[116:119], v[80:95]
	v_add_f32_e32 v251, v42, v251
	v_exp_f32_e32 v44, v44
	v_add_f32_e32 v251, v43, v251
	v_cvt_pk_bf16_f32 v53, v58, v59
	v_exp_f32_e32 v45, v45
	v_add_f32_e32 v251, v44, v251
	v_mfma_f32_32x32x16_bf16 v[64:79], v[136:139], v[120:123], v[64:79]
	v_exp_f32_e32 v46, v46
	v_add_f32_e32 v251, v45, v251
	v_cvt_pk_bf16_f32 v54, v60, v61
	v_exp_f32_e32 v47, v47
	v_add_f32_e32 v251, v46, v251
	v_add_f32_e32 v251, v47, v251
	v_cvt_pk_bf16_f32 v55, v62, v63
	v_cvt_pk_bf16_f32 v32, v32, v33
	s_waitcnt lgkmcnt(10)
	v_mfma_f32_32x32x16_bf16 v[80:95], v[144:147], v[120:123], v[80:95]
	v_cvt_pk_bf16_f32 v33, v34, v35
	v_cvt_pk_bf16_f32 v34, v36, v37
	v_cvt_pk_bf16_f32 v35, v38, v39
	v_cvt_pk_bf16_f32 v36, v40, v41
	v_cvt_pk_bf16_f32 v37, v42, v43
	v_cvt_pk_bf16_f32 v38, v44, v45
	v_cvt_pk_bf16_f32 v39, v46, v47
	v_add_f32_e32 v195, v195, v251
	v_add_f32_e32 v199, v199, v195
	s_waitcnt lgkmcnt(0)
	s_barrier

	v_add_u32_e32 v197, s6, v204
	v_mfma_f32_32x32x16_bf16 v[0:15], v[48:51], v[210:213], v[0:15]
	ds_read_b128 v[172:175], v197
	ds_read_b128 v[152:155], v197 offset:32
	v_mfma_f32_32x32x16_bf16 v[0:15], v[52:55], v[222:225], v[0:15]
	ds_read_b128 v[180:183], v197 offset:6656
	ds_read_b128 v[164:167], v197 offset:6688
	v_mfma_f32_32x32x16_bf16 v[0:15], v[32:35], v[230:233], v[0:15]
	ds_read_b128 v[156:159], v197 offset:64
	ds_read_b128 v[140:143], v197 offset:96
	v_mfma_f32_32x32x16_bf16 v[0:15], v[36:39], v[238:241], v[0:15]
	ds_read_b128 v[176:179], v197 offset:6720
	ds_read_b128 v[160:163], v197 offset:6752
	v_mfma_f32_32x32x16_bf16 v[16:31], v[48:51], v[214:217], v[16:31]
	ds_read_b128 v[148:151], v197 offset:128
	ds_read_b128 v[136:139], v197 offset:160
	v_mfma_f32_32x32x16_bf16 v[16:31], v[52:55], v[218:221], v[16:31]
	ds_read_b128 v[168:171], v197 offset:6784
	ds_read_b128 v[144:147], v197 offset:6816
	v_mfma_f32_32x32x16_bf16 v[16:31], v[32:35], v[226:229], v[16:31]
	v_mfma_f32_32x32x16_bf16 v[16:31], v[36:39], v[234:237], v[16:31]
	s_barrier
	s_waitcnt lgkmcnt(11)
	v_mfma_f32_32x32x16_bf16 v[48:63], v[172:175], v[100:103], 0
	v_exp_f32_e32 v64, v64
	v_exp_f32_e32 v65, v65
	v_exp_f32_e32 v66, v66
	v_add_f32_e32 v195, v64, v65
	v_exp_f32_e32 v67, v67
	s_waitcnt lgkmcnt(9)
	v_mfma_f32_32x32x16_bf16 v[32:47], v[180:183], v[100:103], 0
	v_add_f32_e32 v195, v66, v195
	v_exp_f32_e32 v68, v68
	v_add_f32_e32 v195, v67, v195
	v_exp_f32_e32 v69, v69
	v_add_f32_e32 v195, v68, v195
	v_exp_f32_e32 v70, v70
	v_add_f32_e32 v195, v69, v195
	v_mfma_f32_32x32x16_bf16 v[48:63], v[152:155], v[104:107], v[48:63]
	v_exp_f32_e32 v71, v71
	v_add_f32_e32 v195, v70, v195
	v_exp_f32_e32 v72, v72
	v_add_f32_e32 v195, v71, v195
	v_exp_f32_e32 v73, v73
	v_add_f32_e32 v195, v72, v195
	s_waitcnt lgkmcnt(8)
	v_mfma_f32_32x32x16_bf16 v[32:47], v[164:167], v[104:107], v[32:47]
	v_exp_f32_e32 v74, v74
	v_add_f32_e32 v195, v73, v195
	v_exp_f32_e32 v75, v75
	v_add_f32_e32 v195, v74, v195
	v_exp_f32_e32 v76, v76
	v_add_f32_e32 v195, v75, v195
	s_waitcnt lgkmcnt(7)
	v_mfma_f32_32x32x16_bf16 v[48:63], v[156:159], v[108:111], v[48:63]
	v_exp_f32_e32 v77, v77
	v_add_f32_e32 v195, v76, v195
	v_exp_f32_e32 v78, v78
	v_add_f32_e32 v195, v77, v195
	v_exp_f32_e32 v79, v79
	v_add_f32_e32 v195, v78, v195
	v_add_f32_e32 v195, v79, v195
	s_add_i32 s4, s91, 1
	s_cmp_lg_u32 s91, 2
	s_cselect_b32 s74, s4, 0
	s_mul_i32 s6, s74, 0x3400
	s_add_i32 s7, s6, 0
	s_add_u32 s98, s98, 0x3000
	s_addc_u32 s99, s99, 0

	v_add_u32_e32 v253, s7, v96
	s_waitcnt vmcnt(1)
	ds_write_b128 v253, v[128:131]
	s_and_saveexec_b64 s[4:5], s[2:3]
	v_add_u32_e32 v253, s7, v185
	ds_write_b128 v253, v[124:127]
	s_or_b64 exec, exec, s[4:5]
	v_lshl_add_u64 v[200:201], s[100:101], 0, v[190:191]

	s_waitcnt vmcnt(0)
	ds_write2_b64 v205, v[132:133], v[134:135] offset0:128 offset1:130
	v_lshl_add_u64 v[128:129], s[98:99], 0, v[188:189]
	s_nop 0
	global_load_dwordx4 v[128:131], v[128:129], off

	s_and_saveexec_b64 s[4:5], s[2:3]
	s_cbranch_execz .Lat7A_A_h1
	v_lshl_add_u64 v[124:125], s[98:99], 0, v[186:187]
	s_nop 0
	global_load_dwordx4 v[124:127], v[124:125], off
.Lat7A_A_h1:
	s_or_b64 exec, exec, s[4:5]
	global_load_dwordx4 v[132:135], v[200:201], off offset:384

	s_sub_u32 s98, s98, 0x3000
	s_subb_u32 s99, s99, 0

	s_waitcnt lgkmcnt(7)
	v_mfma_f32_32x32x16_bf16 v[32:47], v[176:179], v[108:111], v[32:47]
	v_exp_f32_e32 v80, v80
	v_exp_f32_e32 v81, v81
	v_exp_f32_e32 v82, v82
	v_add_f32_e32 v251, v80, v81
	v_cvt_pk_bf16_f32 v64, v64, v65
	v_exp_f32_e32 v83, v83
	v_mfma_f32_32x32x16_bf16 v[48:63], v[140:143], v[112:115], v[48:63]
	v_add_f32_e32 v251, v82, v251
	v_exp_f32_e32 v84, v84
	v_add_f32_e32 v251, v83, v251
	v_cvt_pk_bf16_f32 v65, v66, v67
	v_exp_f32_e32 v85, v85
	v_add_f32_e32 v251, v84, v251
	s_waitcnt lgkmcnt(6)
	v_mfma_f32_32x32x16_bf16 v[32:47], v[160:163], v[112:115], v[32:47]
	v_exp_f32_e32 v86, v86
	v_add_f32_e32 v251, v85, v251
	v_cvt_pk_bf16_f32 v66, v68, v69
	v_exp_f32_e32 v87, v87
	v_add_f32_e32 v251, v86, v251
	v_exp_f32_e32 v88, v88
	v_add_f32_e32 v251, v87, v251
	s_waitcnt lgkmcnt(5)
	v_mfma_f32_32x32x16_bf16 v[48:63], v[148:151], v[116:119], v[48:63]
	v_cvt_pk_bf16_f32 v67, v70, v71
	v_exp_f32_e32 v89, v89
	v_add_f32_e32 v251, v88, v251
	v_exp_f32_e32 v90, v90
	v_add_f32_e32 v251, v89, v251
	v_cvt_pk_bf16_f32 v68, v72, v73
	v_exp_f32_e32 v91, v91
	v_add_u32_e32 v198, v207, v184
	ds_read_b128 v[210:213], v198 offset:53760
	ds_read_b128 v[214:217], v198 offset:49152
	ds_read_b128 v[218:221], v198 offset:49184
	ds_read_b128 v[222:225], v198 offset:53792
	ds_read_b128 v[226:229], v198 offset:49216
	ds_read_b128 v[230:233], v198 offset:53824
	ds_read_b128 v[234:237], v198 offset:49248
	ds_read_b128 v[238:241], v198 offset:53856
	s_waitcnt lgkmcnt(11)
	v_mfma_f32_32x32x16_bf16 v[32:47], v[168:171], v[116:119], v[32:47]
	v_add_f32_e32 v251, v90, v251
	v_exp_f32_e32 v92, v92
	v_add_f32_e32 v251, v91, v251
	v_cvt_pk_bf16_f32 v69, v74, v75
	v_exp_f32_e32 v93, v93
	v_add_f32_e32 v251, v92, v251
	v_mfma_f32_32x32x16_bf16 v[48:63], v[136:139], v[120:123], v[48:63]
	v_exp_f32_e32 v94, v94
	v_add_f32_e32 v251, v93, v251
	v_cvt_pk_bf16_f32 v70, v76, v77
	v_exp_f32_e32 v95, v95
	v_add_f32_e32 v251, v94, v251
	v_add_f32_e32 v251, v95, v251
	v_cvt_pk_bf16_f32 v71, v78, v79
	v_cvt_pk_bf16_f32 v80, v80, v81
	s_waitcnt lgkmcnt(10)
	v_mfma_f32_32x32x16_bf16 v[32:47], v[144:147], v[120:123], v[32:47]
	v_cvt_pk_bf16_f32 v81, v82, v83
	v_cvt_pk_bf16_f32 v82, v84, v85
	v_cvt_pk_bf16_f32 v83, v86, v87
	v_cvt_pk_bf16_f32 v84, v88, v89
	v_cvt_pk_bf16_f32 v85, v90, v91
	v_cvt_pk_bf16_f32 v86, v92, v93
	v_cvt_pk_bf16_f32 v87, v94, v95
	v_add_f32_e32 v195, v195, v251
	v_add_f32_e32 v199, v199, v195
	s_add_i32 s92, s79, 2
	s_waitcnt lgkmcnt(0)
	s_barrier

	v_add_u32_e32 v197, s6, v204
	v_mfma_f32_32x32x16_bf16 v[0:15], v[64:67], v[210:213], v[0:15]
	ds_read_b128 v[172:175], v197
	ds_read_b128 v[152:155], v197 offset:32
	v_mfma_f32_32x32x16_bf16 v[0:15], v[68:71], v[222:225], v[0:15]
	ds_read_b128 v[180:183], v197 offset:6656
	ds_read_b128 v[164:167], v197 offset:6688
	v_mfma_f32_32x32x16_bf16 v[0:15], v[80:83], v[230:233], v[0:15]
	ds_read_b128 v[156:159], v197 offset:64
	ds_read_b128 v[140:143], v197 offset:96
	v_mfma_f32_32x32x16_bf16 v[0:15], v[84:87], v[238:241], v[0:15]
	ds_read_b128 v[176:179], v197 offset:6720
	ds_read_b128 v[160:163], v197 offset:6752
	v_mfma_f32_32x32x16_bf16 v[16:31], v[64:67], v[214:217], v[16:31]
	ds_read_b128 v[148:151], v197 offset:128
	ds_read_b128 v[136:139], v197 offset:160
	v_mfma_f32_32x32x16_bf16 v[16:31], v[68:71], v[218:221], v[16:31]
	ds_read_b128 v[168:171], v197 offset:6784
	ds_read_b128 v[144:147], v197 offset:6816
	v_mfma_f32_32x32x16_bf16 v[16:31], v[80:83], v[226:229], v[16:31]
	v_mfma_f32_32x32x16_bf16 v[16:31], v[84:87], v[234:237], v[16:31]
	s_barrier
	s_add_i32 s4, s74, 1
	s_cmp_lg_u32 s74, 2
	s_cselect_b32 s91, s4, 0
	s_add_i32 s4, s93, 0x80
	v_lshl_add_u64 v[188:189], v[188:189], 0, s[82:83]
	v_lshl_add_u64 v[186:187], v[186:187], 0, s[82:83]
	v_lshl_add_u64 v[190:191], v[190:191], 0, s[66:67]
	v_lshl_add_u64 v[192:193], v[98:99], 0, s[66:67]

	s_cmp_ge_u32 s92, s87
	s_cbranch_scc1 .Lst7A_Aexit

	v_mov_b64_e32 v[98:99], v[192:193]
	s_mov_b32 s93, s4
	s_mov_b32 s79, s92

	s_branch .LBB0_1039
.Lst7A_Aexit:
	s_barrier
	s_branch .LBB0_1049
.Lst7A_Lentry:

	s_mul_i32 s6, s91, 0x3400
	s_add_i32 s7, s6, 0

	v_add_u32_e32 v253, s7, v96
	s_waitcnt vmcnt(1)
	ds_write_b128 v253, v[128:131]
	s_and_saveexec_b64 s[4:5], s[2:3]
	v_add_u32_e32 v253, s7, v185
	ds_write_b128 v253, v[124:127]
	s_or_b64 exec, exec, s[4:5]
	v_lshl_add_u64 v[200:201], s[100:101], 0, v[190:191]

	v_add_u32_e32 v206, 0xc000, v208
	v_lshl_add_u64 v[128:129], s[98:99], 0, v[188:189]
	s_nop 0
	global_load_dwordx4 v[128:131], v[128:129], off
	s_waitcnt vmcnt(1)
	ds_write2_b64 v206, v[132:133], v[134:135] offset1:2

	s_and_saveexec_b64 s[4:5], s[2:3]
	s_cbranch_execz .Lat7A_E_h0
	v_lshl_add_u64 v[124:125], s[98:99], 0, v[186:187]
	s_nop 0
	global_load_dwordx4 v[124:127], v[124:125], off
.Lat7A_E_h0:
	s_or_b64 exec, exec, s[4:5]
	global_load_dwordx4 v[132:135], v[200:201], off offset:256

	s_waitcnt lgkmcnt(0)
	s_barrier
.Lst7A_Lloop:

	s_waitcnt lgkmcnt(11)
	v_mfma_f32_32x32x16_bf16 v[64:79], v[172:175], v[100:103], 0
	v_exp_f32_e32 v48, v48
	v_exp_f32_e32 v49, v49
	v_exp_f32_e32 v50, v50
	v_add_f32_e32 v195, v48, v49
	v_exp_f32_e32 v51, v51
	s_waitcnt lgkmcnt(9)
	v_mfma_f32_32x32x16_bf16 v[80:95], v[180:183], v[100:103], 0
	v_add_f32_e32 v195, v50, v195
	v_exp_f32_e32 v52, v52
	v_add_f32_e32 v195, v51, v195
	v_exp_f32_e32 v53, v53
	v_add_f32_e32 v195, v52, v195
	v_exp_f32_e32 v54, v54
	v_add_f32_e32 v195, v53, v195
	v_mfma_f32_32x32x16_bf16 v[64:79], v[152:155], v[104:107], v[64:79]
	v_exp_f32_e32 v55, v55
	v_add_f32_e32 v195, v54, v195
	v_exp_f32_e32 v56, v56
	v_add_f32_e32 v195, v55, v195
	v_exp_f32_e32 v57, v57
	v_add_f32_e32 v195, v56, v195
	s_waitcnt lgkmcnt(8)
	v_mfma_f32_32x32x16_bf16 v[80:95], v[164:167], v[104:107], v[80:95]
	v_exp_f32_e32 v58, v58
	v_add_f32_e32 v195, v57, v195
	v_exp_f32_e32 v59, v59
	v_add_f32_e32 v195, v58, v195
	v_exp_f32_e32 v60, v60
	v_add_f32_e32 v195, v59, v195
	s_waitcnt lgkmcnt(7)
	v_mfma_f32_32x32x16_bf16 v[64:79], v[156:159], v[108:111], v[64:79]
	v_exp_f32_e32 v61, v61
	v_add_f32_e32 v195, v60, v195
	v_exp_f32_e32 v62, v62
	v_add_f32_e32 v195, v61, v195
	v_exp_f32_e32 v63, v63
	v_add_f32_e32 v195, v62, v195
	v_add_f32_e32 v195, v63, v195
	s_waitcnt lgkmcnt(5)
	v_mfma_f32_32x32x16_bf16 v[80:95], v[176:179], v[108:111], v[80:95]
	v_exp_f32_e32 v32, v32
	v_exp_f32_e32 v33, v33
	v_exp_f32_e32 v34, v34
	v_add_f32_e32 v251, v32, v33
	v_cvt_pk_bf16_f32 v48, v48, v49
	v_exp_f32_e32 v35, v35
	v_mfma_f32_32x32x16_bf16 v[64:79], v[140:143], v[112:115], v[64:79]
	v_add_f32_e32 v251, v34, v251
	v_exp_f32_e32 v36, v36
	v_add_f32_e32 v251, v35, v251
	v_cvt_pk_bf16_f32 v49, v50, v51
	v_exp_f32_e32 v37, v37
	v_add_f32_e32 v251, v36, v251
	s_waitcnt lgkmcnt(4)
	v_mfma_f32_32x32x16_bf16 v[80:95], v[160:163], v[112:115], v[80:95]
	v_exp_f32_e32 v38, v38
	v_add_f32_e32 v251, v37, v251
	v_cvt_pk_bf16_f32 v50, v52, v53
	v_exp_f32_e32 v39, v39
	v_add_f32_e32 v251, v38, v251
	v_exp_f32_e32 v40, v40
	v_add_f32_e32 v251, v39, v251
	s_waitcnt lgkmcnt(3)
	v_mfma_f32_32x32x16_bf16 v[64:79], v[148:151], v[116:119], v[64:79]
	v_cvt_pk_bf16_f32 v51, v54, v55
	v_exp_f32_e32 v41, v41
	v_add_f32_e32 v251, v40, v251
	v_exp_f32_e32 v42, v42
	v_add_f32_e32 v251, v41, v251
	v_cvt_pk_bf16_f32 v52, v56, v57
	v_exp_f32_e32 v43, v43
	v_add_u32_e32 v198, v207, v184
	ds_read_b128 v[210:213], v198 offset:44544
	ds_read_b128 v[214:217], v198 offset:39936
	ds_read_b128 v[218:221], v198 offset:39968
	ds_read_b128 v[222:225], v198 offset:44576
	ds_read_b128 v[226:229], v198 offset:40000
	ds_read_b128 v[230:233], v198 offset:44608
	ds_read_b128 v[234:237], v198 offset:40032
	ds_read_b128 v[238:241], v198 offset:44640
	s_waitcnt lgkmcnt(9)
	v_mfma_f32_32x32x16_bf16 v[80:95], v[168:171], v[116:119], v[80:95]
	v_add_f32_e32 v251, v42, v251
	v_exp_f32_e32 v44, v44
	v_add_f32_e32 v251, v43, v251
	v_cvt_pk_bf16_f32 v53, v58, v59
	v_exp_f32_e32 v45, v45
	v_add_f32_e32 v251, v44, v251
	v_mfma_f32_32x32x16_bf16 v[64:79], v[136:139], v[120:123], v[64:79]
	v_exp_f32_e32 v46, v46
	v_add_f32_e32 v251, v45, v251
	v_cvt_pk_bf16_f32 v54, v60, v61
	v_exp_f32_e32 v47, v47
	v_add_f32_e32 v251, v46, v251
	v_add_f32_e32 v251, v47, v251
	v_cvt_pk_bf16_f32 v55, v62, v63
	v_cvt_pk_bf16_f32 v32, v32, v33
	s_waitcnt lgkmcnt(8)
	v_mfma_f32_32x32x16_bf16 v[80:95], v[144:147], v[120:123], v[80:95]
	v_cvt_pk_bf16_f32 v33, v34, v35
	v_cvt_pk_bf16_f32 v34, v36, v37
	v_cvt_pk_bf16_f32 v35, v38, v39
	v_cvt_pk_bf16_f32 v36, v40, v41
	v_cvt_pk_bf16_f32 v37, v42, v43
	v_cvt_pk_bf16_f32 v38, v44, v45
	v_cvt_pk_bf16_f32 v39, v46, v47
	v_add_f32_e32 v195, v195, v251
	v_add_f32_e32 v199, v199, v195
	s_waitcnt lgkmcnt(0)
	s_barrier

	v_add_u32_e32 v197, s6, v204
	v_mfma_f32_32x32x16_bf16 v[0:15], v[48:51], v[210:213], v[0:15]
	ds_read_b128 v[172:175], v197
	ds_read_b128 v[152:155], v197 offset:32
	v_mfma_f32_32x32x16_bf16 v[0:15], v[52:55], v[222:225], v[0:15]
	ds_read_b128 v[180:183], v197 offset:6656
	ds_read_b128 v[164:167], v197 offset:6688
	v_mfma_f32_32x32x16_bf16 v[0:15], v[32:35], v[230:233], v[0:15]
	ds_read_b128 v[156:159], v197 offset:64
	ds_read_b128 v[140:143], v197 offset:96
	v_mfma_f32_32x32x16_bf16 v[0:15], v[36:39], v[238:241], v[0:15]
	ds_read_b128 v[176:179], v197 offset:6720
	ds_read_b128 v[160:163], v197 offset:6752
	v_mfma_f32_32x32x16_bf16 v[16:31], v[48:51], v[214:217], v[16:31]
	ds_read_b128 v[148:151], v197 offset:128
	ds_read_b128 v[136:139], v197 offset:160
	v_mfma_f32_32x32x16_bf16 v[16:31], v[52:55], v[218:221], v[16:31]
	ds_read_b128 v[168:171], v197 offset:6784
	ds_read_b128 v[144:147], v197 offset:6816
	v_mfma_f32_32x32x16_bf16 v[16:31], v[32:35], v[226:229], v[16:31]
	s_add_i32 s4, s91, 1
	s_cmp_lg_u32 s91, 2
	s_cselect_b32 s74, s4, 0
	s_mul_i32 s6, s74, 0x3400
	s_add_i32 s7, s6, 0
	s_add_u32 s98, s98, 0x3000
	s_addc_u32 s99, s99, 0

	v_add_u32_e32 v253, s7, v96
	s_waitcnt vmcnt(1)
	ds_write_b128 v253, v[128:131]
	s_and_saveexec_b64 s[4:5], s[2:3]
	v_add_u32_e32 v253, s7, v185
	ds_write_b128 v253, v[124:127]
	s_or_b64 exec, exec, s[4:5]
	v_lshl_add_u64 v[200:201], s[100:101], 0, v[190:191]

	s_waitcnt vmcnt(0)
	ds_write2_b64 v205, v[132:133], v[134:135] offset0:128 offset1:130
	v_lshl_add_u64 v[128:129], s[98:99], 0, v[188:189]
	s_nop 0
	global_load_dwordx4 v[128:131], v[128:129], off

	s_and_saveexec_b64 s[4:5], s[2:3]
	s_cbranch_execz .Lat7A_L_h1
	v_lshl_add_u64 v[124:125], s[98:99], 0, v[186:187]
	s_nop 0
	global_load_dwordx4 v[124:127], v[124:125], off
.Lat7A_L_h1:
	s_or_b64 exec, exec, s[4:5]
	global_load_dwordx4 v[132:135], v[200:201], off offset:384

	s_sub_u32 s98, s98, 0x3000
	s_subb_u32 s99, s99, 0

	v_mfma_f32_32x32x16_bf16 v[16:31], v[36:39], v[234:237], v[16:31]
	s_waitcnt lgkmcnt(0)
	s_barrier
	s_waitcnt lgkmcnt(11)
	v_mfma_f32_32x32x16_bf16 v[48:63], v[172:175], v[100:103], 0
	v_exp_f32_e32 v64, v64
	v_exp_f32_e32 v65, v65
	v_exp_f32_e32 v66, v66
	v_add_f32_e32 v195, v64, v65
	v_exp_f32_e32 v67, v67
	s_waitcnt lgkmcnt(9)
	v_mfma_f32_32x32x16_bf16 v[32:47], v[180:183], v[100:103], 0
	v_add_f32_e32 v195, v66, v195
	v_exp_f32_e32 v68, v68
	v_add_f32_e32 v195, v67, v195
	v_exp_f32_e32 v69, v69
	v_add_f32_e32 v195, v68, v195
	v_exp_f32_e32 v70, v70
	v_add_f32_e32 v195, v69, v195
	v_mfma_f32_32x32x16_bf16 v[48:63], v[152:155], v[104:107], v[48:63]
	v_exp_f32_e32 v71, v71
	v_add_f32_e32 v195, v70, v195
	v_exp_f32_e32 v72, v72
	v_add_f32_e32 v195, v71, v195
	v_exp_f32_e32 v73, v73
	v_add_f32_e32 v195, v72, v195
	s_waitcnt lgkmcnt(8)
	v_mfma_f32_32x32x16_bf16 v[32:47], v[164:167], v[104:107], v[32:47]
	v_exp_f32_e32 v74, v74
	v_add_f32_e32 v195, v73, v195
	v_exp_f32_e32 v75, v75
	v_add_f32_e32 v195, v74, v195
	v_exp_f32_e32 v76, v76
	v_add_f32_e32 v195, v75, v195
	s_waitcnt lgkmcnt(7)
	v_mfma_f32_32x32x16_bf16 v[48:63], v[156:159], v[108:111], v[48:63]
	v_exp_f32_e32 v77, v77
	v_add_f32_e32 v195, v76, v195
	v_exp_f32_e32 v78, v78
	v_add_f32_e32 v195, v77, v195
	v_exp_f32_e32 v79, v79
	v_add_f32_e32 v195, v78, v195
	v_add_f32_e32 v195, v79, v195
	s_waitcnt lgkmcnt(5)
	v_mfma_f32_32x32x16_bf16 v[32:47], v[176:179], v[108:111], v[32:47]
	v_exp_f32_e32 v80, v80
	v_exp_f32_e32 v81, v81
	v_exp_f32_e32 v82, v82
	v_add_f32_e32 v251, v80, v81
	v_cvt_pk_bf16_f32 v64, v64, v65
	v_exp_f32_e32 v83, v83
	v_mfma_f32_32x32x16_bf16 v[48:63], v[140:143], v[112:115], v[48:63]
	v_add_f32_e32 v251, v82, v251
	v_exp_f32_e32 v84, v84
	v_add_f32_e32 v251, v83, v251
	v_cvt_pk_bf16_f32 v65, v66, v67
	v_exp_f32_e32 v85, v85
	v_add_f32_e32 v251, v84, v251
	s_waitcnt lgkmcnt(4)
	v_mfma_f32_32x32x16_bf16 v[32:47], v[160:163], v[112:115], v[32:47]
	v_exp_f32_e32 v86, v86
	v_add_f32_e32 v251, v85, v251
	v_cvt_pk_bf16_f32 v66, v68, v69
	v_exp_f32_e32 v87, v87
	v_add_f32_e32 v251, v86, v251
	v_exp_f32_e32 v88, v88
	v_add_f32_e32 v251, v87, v251
	s_waitcnt lgkmcnt(3)
	v_mfma_f32_32x32x16_bf16 v[48:63], v[148:151], v[116:119], v[48:63]
	v_cvt_pk_bf16_f32 v67, v70, v71
	v_exp_f32_e32 v89, v89
	v_add_f32_e32 v251, v88, v251
	v_exp_f32_e32 v90, v90
	v_add_f32_e32 v251, v89, v251
	v_cvt_pk_bf16_f32 v68, v72, v73
	v_exp_f32_e32 v91, v91
	v_add_u32_e32 v198, v207, v184
	ds_read_b128 v[210:213], v198 offset:53760
	ds_read_b128 v[214:217], v198 offset:49152
	ds_read_b128 v[218:221], v198 offset:49184
	ds_read_b128 v[222:225], v198 offset:53792
	ds_read_b128 v[226:229], v198 offset:49216
	ds_read_b128 v[230:233], v198 offset:53824
	ds_read_b128 v[234:237], v198 offset:49248
	ds_read_b128 v[238:241], v198 offset:53856
	s_waitcnt lgkmcnt(9)
	v_mfma_f32_32x32x16_bf16 v[32:47], v[168:171], v[116:119], v[32:47]
	v_add_f32_e32 v251, v90, v251
	v_exp_f32_e32 v92, v92
	v_add_f32_e32 v251, v91, v251
	v_cvt_pk_bf16_f32 v69, v74, v75
	v_exp_f32_e32 v93, v93
	v_add_f32_e32 v251, v92, v251
	v_mfma_f32_32x32x16_bf16 v[48:63], v[136:139], v[120:123], v[48:63]
	v_exp_f32_e32 v94, v94
	v_add_f32_e32 v251, v93, v251
	v_cvt_pk_bf16_f32 v70, v76, v77
	v_exp_f32_e32 v95, v95
	v_add_f32_e32 v251, v94, v251
	v_add_f32_e32 v251, v95, v251
	v_cvt_pk_bf16_f32 v71, v78, v79
	v_cvt_pk_bf16_f32 v80, v80, v81
	s_waitcnt lgkmcnt(8)
	v_mfma_f32_32x32x16_bf16 v[32:47], v[144:147], v[120:123], v[32:47]
	v_cvt_pk_bf16_f32 v81, v82, v83
	v_cvt_pk_bf16_f32 v82, v84, v85
	v_cvt_pk_bf16_f32 v83, v86, v87
	v_cvt_pk_bf16_f32 v84, v88, v89
	v_cvt_pk_bf16_f32 v85, v90, v91
	v_cvt_pk_bf16_f32 v86, v92, v93
	v_cvt_pk_bf16_f32 v87, v94, v95
	v_add_f32_e32 v195, v195, v251
	v_add_f32_e32 v199, v199, v195
	s_add_i32 s92, s79, 2
	s_waitcnt lgkmcnt(0)
	s_barrier

	v_add_u32_e32 v197, s6, v204
	v_mfma_f32_32x32x16_bf16 v[0:15], v[64:67], v[210:213], v[0:15]
	ds_read_b128 v[172:175], v197
	ds_read_b128 v[152:155], v197 offset:32
	v_mfma_f32_32x32x16_bf16 v[0:15], v[68:71], v[222:225], v[0:15]
	ds_read_b128 v[180:183], v197 offset:6656
	ds_read_b128 v[164:167], v197 offset:6688
	v_mfma_f32_32x32x16_bf16 v[0:15], v[80:83], v[230:233], v[0:15]
	ds_read_b128 v[156:159], v197 offset:64
	ds_read_b128 v[140:143], v197 offset:96
	v_mfma_f32_32x32x16_bf16 v[0:15], v[84:87], v[238:241], v[0:15]
	ds_read_b128 v[176:179], v197 offset:6720
	ds_read_b128 v[160:163], v197 offset:6752
	v_mfma_f32_32x32x16_bf16 v[16:31], v[64:67], v[214:217], v[16:31]
	ds_read_b128 v[148:151], v197 offset:128
	ds_read_b128 v[136:139], v197 offset:160
	v_mfma_f32_32x32x16_bf16 v[16:31], v[68:71], v[218:221], v[16:31]
	ds_read_b128 v[168:171], v197 offset:6784
	ds_read_b128 v[144:147], v197 offset:6816
	v_mfma_f32_32x32x16_bf16 v[16:31], v[80:83], v[226:229], v[16:31]
	s_add_i32 s4, s74, 1
	s_cmp_lg_u32 s74, 2
	s_cselect_b32 s91, s4, 0
	s_add_i32 s4, s93, 0x80
	v_lshl_add_u64 v[188:189], v[188:189], 0, s[82:83]
	v_lshl_add_u64 v[186:187], v[186:187], 0, s[82:83]
	v_lshl_add_u64 v[190:191], v[190:191], 0, s[66:67]
	v_lshl_add_u64 v[192:193], v[98:99], 0, s[66:67]

	s_cmp_ge_u32 s92, s87
	s_cbranch_scc1 .Lst7A_Lskip

	v_mov_b64_e32 v[98:99], v[192:193]
	s_mov_b32 s93, s4
	s_mov_b32 s79, s92

	s_mul_i32 s6, s91, 0x3400
	s_add_i32 s7, s6, 0

	v_add_u32_e32 v253, s7, v96
	s_waitcnt vmcnt(1)
	ds_write_b128 v253, v[128:131]
	s_and_saveexec_b64 s[4:5], s[2:3]
	v_add_u32_e32 v253, s7, v185
	ds_write_b128 v253, v[124:127]
	s_or_b64 exec, exec, s[4:5]
	v_lshl_add_u64 v[200:201], s[100:101], 0, v[190:191]

	v_add_u32_e32 v206, 0xc000, v208
	v_lshl_add_u64 v[128:129], s[98:99], 0, v[188:189]
	s_nop 0
	global_load_dwordx4 v[128:131], v[128:129], off
	s_waitcnt vmcnt(1)
	ds_write2_b64 v206, v[132:133], v[134:135] offset1:2

	s_and_saveexec_b64 s[4:5], s[2:3]
	s_cbranch_execz .Lat7A_L_h0
	v_lshl_add_u64 v[124:125], s[98:99], 0, v[186:187]
	s_nop 0
	global_load_dwordx4 v[124:127], v[124:125], off

.Lst7A_Lskip:
	v_mfma_f32_32x32x16_bf16 v[16:31], v[84:87], v[234:237], v[16:31]
	s_waitcnt lgkmcnt(0)
	s_barrier
	s_cmp_ge_u32 s92, s87
	s_cbranch_scc0 .Lst7A_Lloop
	s_branch .LBB0_1049


.LBB0_1106:
	s_getreg_b32 s4, hwreg(HW_REG_HW_ID, 0, 6)
	s_and_b32 s4, s4, 63
	s_lshl_b32 s4, s4, 2
	s_add_i32 s4, s4, 0x20840
	v_mov_b32_e32 v253, s4
	ds_read_b32 v253, v253
	s_waitcnt lgkmcnt(0)
	v_readfirstlane_b32 s4, v253
	s_cmp_ge_u32 s4, 4
	s_cbranch_scc1 .Lst7B_Lentry


.Lat7B_A_h0:
	s_or_b64 exec, exec, s[4:5]
	global_load_dwordx4 v[132:135], v[200:201], off offset:256

	s_waitcnt lgkmcnt(7)
	v_mfma_f32_32x32x16_bf16 v[80:95], v[176:179], v[108:111], v[80:95]
	v_exp_f32_e32 v32, v32
	v_exp_f32_e32 v33, v33
	v_exp_f32_e32 v34, v34
	v_add_f32_e32 v251, v32, v33
	v_cvt_pk_bf16_f32 v48, v48, v49
	v_exp_f32_e32 v35, v35
	v_mfma_f32_32x32x16_bf16 v[64:79], v[140:143], v[112:115], v[64:79]
	v_add_f32_e32 v251, v34, v251
	v_exp_f32_e32 v36, v36
	v_add_f32_e32 v251, v35, v251
	v_cvt_pk_bf16_f32 v49, v50, v51
	v_exp_f32_e32 v37, v37
	v_add_f32_e32 v251, v36, v251
	s_waitcnt lgkmcnt(6)
	v_mfma_f32_32x32x16_bf16 v[80:95], v[160:163], v[112:115], v[80:95]
	v_exp_f32_e32 v38, v38
	v_add_f32_e32 v251, v37, v251
	v_cvt_pk_bf16_f32 v50, v52, v53
	v_exp_f32_e32 v39, v39
	v_add_f32_e32 v251, v38, v251
	v_exp_f32_e32 v40, v40
	v_add_f32_e32 v251, v39, v251
	s_waitcnt lgkmcnt(5)
	v_mfma_f32_32x32x16_bf16 v[64:79], v[148:151], v[116:119], v[64:79]
	v_cvt_pk_bf16_f32 v51, v54, v55
	v_exp_f32_e32 v41, v41
	v_add_f32_e32 v251, v40, v251
	v_exp_f32_e32 v42, v42
	v_add_f32_e32 v251, v41, v251
	v_cvt_pk_bf16_f32 v52, v56, v57
	v_exp_f32_e32 v43, v43
	v_add_u32_e32 v196, v208, v184
	ds_read_b128 v[212:215], v196 offset:44544
	ds_read_b128 v[216:219], v196 offset:39936
	ds_read_b128 v[220:223], v196 offset:39968
	ds_read_b128 v[224:227], v196 offset:44576
	ds_read_b128 v[228:231], v196 offset:40000
	ds_read_b128 v[232:235], v196 offset:44608
	ds_read_b128 v[236:239], v196 offset:40032
	ds_read_b128 v[240:243], v196 offset:44640
	s_waitcnt lgkmcnt(11)
	v_mfma_f32_32x32x16_bf16 v[80:95], v[168:171], v[116:119], v[80:95]
	v_add_f32_e32 v251, v42, v251
	v_exp_f32_e32 v44, v44
	v_add_f32_e32 v251, v43, v251
	v_cvt_pk_bf16_f32 v53, v58, v59
	v_exp_f32_e32 v45, v45
	v_add_f32_e32 v251, v44, v251
	v_mfma_f32_32x32x16_bf16 v[64:79], v[136:139], v[120:123], v[64:79]
	v_exp_f32_e32 v46, v46
	v_add_f32_e32 v251, v45, v251
	v_cvt_pk_bf16_f32 v54, v60, v61
	v_exp_f32_e32 v47, v47
	v_add_f32_e32 v251, v46, v251
	v_add_f32_e32 v251, v47, v251
	v_cvt_pk_bf16_f32 v55, v62, v63
	v_cvt_pk_bf16_f32 v32, v32, v33
	s_waitcnt lgkmcnt(10)
	v_mfma_f32_32x32x16_bf16 v[80:95], v[144:147], v[120:123], v[80:95]
	v_cvt_pk_bf16_f32 v33, v34, v35
	v_cvt_pk_bf16_f32 v34, v36, v37
	v_cvt_pk_bf16_f32 v35, v38, v39
	v_cvt_pk_bf16_f32 v36, v40, v41
	v_cvt_pk_bf16_f32 v37, v42, v43
	v_cvt_pk_bf16_f32 v38, v44, v45
	v_cvt_pk_bf16_f32 v39, v46, v47
	v_add_f32_e32 v195, v195, v251
	v_add_f32_e32 v198, v198, v195
	s_waitcnt lgkmcnt(0)
	s_barrier

	v_add_u32_e32 v197, s6, v209
	v_mfma_f32_32x32x16_bf16 v[0:15], v[48:51], v[212:215], v[0:15]
	ds_read_b128 v[172:175], v197
	ds_read_b128 v[152:155], v197 offset:32
	v_mfma_f32_32x32x16_bf16 v[0:15], v[52:55], v[224:227], v[0:15]
	ds_read_b128 v[180:183], v197 offset:6656
	ds_read_b128 v[164:167], v197 offset:6688
	v_mfma_f32_32x32x16_bf16 v[0:15], v[32:35], v[232:235], v[0:15]
	ds_read_b128 v[156:159], v197 offset:64
	ds_read_b128 v[140:143], v197 offset:96
	v_mfma_f32_32x32x16_bf16 v[0:15], v[36:39], v[240:243], v[0:15]
	ds_read_b128 v[176:179], v197 offset:6720
	ds_read_b128 v[160:163], v197 offset:6752
	v_mfma_f32_32x32x16_bf16 v[16:31], v[48:51], v[216:219], v[16:31]
	ds_read_b128 v[148:151], v197 offset:128
	ds_read_b128 v[136:139], v197 offset:160
	v_mfma_f32_32x32x16_bf16 v[16:31], v[52:55], v[220:223], v[16:31]
	ds_read_b128 v[168:171], v197 offset:6784
	ds_read_b128 v[144:147], v197 offset:6816
	v_mfma_f32_32x32x16_bf16 v[16:31], v[32:35], v[228:231], v[16:31]
	v_mfma_f32_32x32x16_bf16 v[16:31], v[36:39], v[236:239], v[16:31]
	s_barrier
	s_waitcnt lgkmcnt(11)
	v_mfma_f32_32x32x16_bf16 v[48:63], v[172:175], v[100:103], 0
	v_exp_f32_e32 v64, v64
	v_exp_f32_e32 v65, v65
	v_exp_f32_e32 v66, v66
	v_add_f32_e32 v195, v64, v65
	v_exp_f32_e32 v67, v67
	s_waitcnt lgkmcnt(9)
	v_mfma_f32_32x32x16_bf16 v[32:47], v[180:183], v[100:103], 0
	v_add_f32_e32 v195, v66, v195
	v_exp_f32_e32 v68, v68
	v_add_f32_e32 v195, v67, v195
	v_exp_f32_e32 v69, v69
	v_add_f32_e32 v195, v68, v195
	v_exp_f32_e32 v70, v70
	v_add_f32_e32 v195, v69, v195
	v_mfma_f32_32x32x16_bf16 v[48:63], v[152:155], v[104:107], v[48:63]
	v_exp_f32_e32 v71, v71
	v_add_f32_e32 v195, v70, v195
	v_exp_f32_e32 v72, v72
	v_add_f32_e32 v195, v71, v195
	v_exp_f32_e32 v73, v73
	v_add_f32_e32 v195, v72, v195
	s_waitcnt lgkmcnt(8)
	v_mfma_f32_32x32x16_bf16 v[32:47], v[164:167], v[104:107], v[32:47]
	v_exp_f32_e32 v74, v74
	v_add_f32_e32 v195, v73, v195
	v_exp_f32_e32 v75, v75
	v_add_f32_e32 v195, v74, v195
	v_exp_f32_e32 v76, v76
	v_add_f32_e32 v195, v75, v195
	s_waitcnt lgkmcnt(7)
	v_mfma_f32_32x32x16_bf16 v[48:63], v[156:159], v[108:111], v[48:63]
	v_exp_f32_e32 v77, v77
	v_add_f32_e32 v195, v76, v195
	v_exp_f32_e32 v78, v78
	v_add_f32_e32 v195, v77, v195
	v_exp_f32_e32 v79, v79
	v_add_f32_e32 v195, v78, v195
	v_add_f32_e32 v195, v79, v195
	s_add_i32 s4, s90, 1
	s_cmp_lg_u32 s90, 2
	s_cselect_b32 s68, s4, 0
	s_mul_i32 s6, s68, 0x3400
	s_add_i32 s7, s6, 0
	s_add_u32 s98, s98, 0x3000
	s_addc_u32 s99, s99, 0

	v_add_u32_e32 v253, s7, v96
	s_waitcnt vmcnt(1)
	ds_write_b128 v253, v[128:131]
	s_and_saveexec_b64 s[4:5], s[2:3]
	v_add_u32_e32 v253, s7, v185
	ds_write_b128 v253, v[124:127]
	s_or_b64 exec, exec, s[4:5]
	v_lshl_add_u64 v[200:201], s[100:101], 0, v[204:205]

	s_waitcnt vmcnt(0)
	ds_write2_b64 v211, v[132:133], v[134:135] offset0:128 offset1:130
	v_lshl_add_u64 v[128:129], s[98:99], 0, v[98:99]
	s_nop 0
	global_load_dwordx4 v[128:131], v[128:129], off

	s_and_saveexec_b64 s[4:5], s[2:3]
	s_cbranch_execz .Lat7B_A_h1
	v_lshl_add_u64 v[124:125], s[98:99], 0, v[202:203]
	s_nop 0
	global_load_dwordx4 v[124:127], v[124:125], off
.Lat7B_A_h1:
	s_or_b64 exec, exec, s[4:5]
	global_load_dwordx4 v[132:135], v[200:201], off offset:384

	s_sub_u32 s98, s98, 0x3000
	s_subb_u32 s99, s99, 0

	s_waitcnt lgkmcnt(7)
	v_mfma_f32_32x32x16_bf16 v[32:47], v[176:179], v[108:111], v[32:47]
	v_exp_f32_e32 v80, v80
	v_exp_f32_e32 v81, v81
	v_exp_f32_e32 v82, v82
	v_add_f32_e32 v251, v80, v81
	v_cvt_pk_bf16_f32 v64, v64, v65
	v_exp_f32_e32 v83, v83
	v_mfma_f32_32x32x16_bf16 v[48:63], v[140:143], v[112:115], v[48:63]
	v_add_f32_e32 v251, v82, v251
	v_exp_f32_e32 v84, v84
	v_add_f32_e32 v251, v83, v251
	v_cvt_pk_bf16_f32 v65, v66, v67
	v_exp_f32_e32 v85, v85
	v_add_f32_e32 v251, v84, v251
	s_waitcnt lgkmcnt(6)
	v_mfma_f32_32x32x16_bf16 v[32:47], v[160:163], v[112:115], v[32:47]
	v_exp_f32_e32 v86, v86
	v_add_f32_e32 v251, v85, v251
	v_cvt_pk_bf16_f32 v66, v68, v69
	v_exp_f32_e32 v87, v87
	v_add_f32_e32 v251, v86, v251
	v_exp_f32_e32 v88, v88
	v_add_f32_e32 v251, v87, v251
	s_waitcnt lgkmcnt(5)
	v_mfma_f32_32x32x16_bf16 v[48:63], v[148:151], v[116:119], v[48:63]
	v_cvt_pk_bf16_f32 v67, v70, v71
	v_exp_f32_e32 v89, v89
	v_add_f32_e32 v251, v88, v251
	v_exp_f32_e32 v90, v90
	v_add_f32_e32 v251, v89, v251
	v_cvt_pk_bf16_f32 v68, v72, v73
	v_exp_f32_e32 v91, v91
	v_add_u32_e32 v196, v208, v184
	ds_read_b128 v[212:215], v196 offset:53760
	ds_read_b128 v[216:219], v196 offset:49152
	ds_read_b128 v[220:223], v196 offset:49184
	ds_read_b128 v[224:227], v196 offset:53792
	ds_read_b128 v[228:231], v196 offset:49216
	ds_read_b128 v[232:235], v196 offset:53824
	ds_read_b128 v[236:239], v196 offset:49248
	ds_read_b128 v[240:243], v196 offset:53856
	s_waitcnt lgkmcnt(11)
	v_mfma_f32_32x32x16_bf16 v[32:47], v[168:171], v[116:119], v[32:47]
	v_add_f32_e32 v251, v90, v251
	v_exp_f32_e32 v92, v92
	v_add_f32_e32 v251, v91, v251
	v_cvt_pk_bf16_f32 v69, v74, v75
	v_exp_f32_e32 v93, v93
	v_add_f32_e32 v251, v92, v251
	v_mfma_f32_32x32x16_bf16 v[48:63], v[136:139], v[120:123], v[48:63]
	v_exp_f32_e32 v94, v94
	v_add_f32_e32 v251, v93, v251
	v_cvt_pk_bf16_f32 v70, v76, v77
	v_exp_f32_e32 v95, v95
	v_add_f32_e32 v251, v94, v251
	v_add_f32_e32 v251, v95, v251
	v_cvt_pk_bf16_f32 v71, v78, v79
	v_cvt_pk_bf16_f32 v80, v80, v81
	s_waitcnt lgkmcnt(10)
	v_mfma_f32_32x32x16_bf16 v[32:47], v[144:147], v[120:123], v[32:47]
	v_cvt_pk_bf16_f32 v81, v82, v83
	v_cvt_pk_bf16_f32 v82, v84, v85
	v_cvt_pk_bf16_f32 v83, v86, v87
	v_cvt_pk_bf16_f32 v84, v88, v89
	v_cvt_pk_bf16_f32 v85, v90, v91
	v_cvt_pk_bf16_f32 v86, v92, v93
	v_cvt_pk_bf16_f32 v87, v94, v95
	v_add_f32_e32 v195, v195, v251
	v_add_f32_e32 v198, v198, v195
	s_add_i32 s40, s40, 2
	s_waitcnt lgkmcnt(0)
	s_barrier

	v_add_u32_e32 v197, s6, v209
	v_mfma_f32_32x32x16_bf16 v[0:15], v[64:67], v[212:215], v[0:15]
	ds_read_b128 v[172:175], v197
	ds_read_b128 v[152:155], v197 offset:32
	v_mfma_f32_32x32x16_bf16 v[0:15], v[68:71], v[224:227], v[0:15]
	ds_read_b128 v[180:183], v197 offset:6656
	ds_read_b128 v[164:167], v197 offset:6688
	v_mfma_f32_32x32x16_bf16 v[0:15], v[80:83], v[232:235], v[0:15]
	ds_read_b128 v[156:159], v197 offset:64
	ds_read_b128 v[140:143], v197 offset:96
	v_mfma_f32_32x32x16_bf16 v[0:15], v[84:87], v[240:243], v[0:15]
	ds_read_b128 v[176:179], v197 offset:6720
	ds_read_b128 v[160:163], v197 offset:6752
	v_mfma_f32_32x32x16_bf16 v[16:31], v[64:67], v[216:219], v[16:31]
	ds_read_b128 v[148:151], v197 offset:128
	ds_read_b128 v[136:139], v197 offset:160
	v_mfma_f32_32x32x16_bf16 v[16:31], v[68:71], v[220:223], v[16:31]
	ds_read_b128 v[168:171], v197 offset:6784
	ds_read_b128 v[144:147], v197 offset:6816
	v_mfma_f32_32x32x16_bf16 v[16:31], v[80:83], v[228:231], v[16:31]
	v_mfma_f32_32x32x16_bf16 v[16:31], v[84:87], v[236:239], v[16:31]
	s_barrier
	s_add_i32 s4, s68, 1
	s_cmp_lg_u32 s68, 2
	s_cselect_b32 s90, s4, 0
	v_lshl_add_u64 v[98:99], v[98:99], 0, s[82:83]
	v_lshl_add_u64 v[202:203], v[202:203], 0, s[82:83]
	v_lshl_add_u64 v[204:205], v[204:205], 0, s[66:67]

	s_cmp_ge_u32 s40, s69
	s_cbranch_scc0 .Lst7B_Aloop
	s_barrier
	s_branch .LBB0_1115
.Lst7B_Lentry:

	s_mul_i32 s6, s90, 0x3400
	s_add_i32 s7, s6, 0

	v_add_u32_e32 v253, s7, v96
	s_waitcnt vmcnt(1)
	ds_write_b128 v253, v[128:131]
	s_and_saveexec_b64 s[4:5], s[2:3]
	v_add_u32_e32 v253, s7, v185
	ds_write_b128 v253, v[124:127]
	s_or_b64 exec, exec, s[4:5]
	v_lshl_add_u64 v[200:201], s[100:101], 0, v[204:205]

	v_add_u32_e32 v254, 0xc000, v210
	v_lshl_add_u64 v[128:129], s[98:99], 0, v[98:99]
	s_nop 0
	global_load_dwordx4 v[128:131], v[128:129], off
	s_waitcnt vmcnt(1)
	ds_write2_b64 v254, v[132:133], v[134:135] offset1:2

	s_and_saveexec_b64 s[4:5], s[2:3]
	s_cbranch_execz .Lat7B_E_h0
	v_lshl_add_u64 v[124:125], s[98:99], 0, v[202:203]
	s_nop 0
	global_load_dwordx4 v[124:127], v[124:125], off

.Lst7B_Lloop:

	s_waitcnt lgkmcnt(11)
	v_mfma_f32_32x32x16_bf16 v[64:79], v[172:175], v[100:103], 0
	v_exp_f32_e32 v48, v48
	v_exp_f32_e32 v49, v49
	v_exp_f32_e32 v50, v50
	v_add_f32_e32 v195, v48, v49
	v_exp_f32_e32 v51, v51
	s_waitcnt lgkmcnt(9)
	v_mfma_f32_32x32x16_bf16 v[80:95], v[180:183], v[100:103], 0
	v_add_f32_e32 v195, v50, v195
	v_exp_f32_e32 v52, v52
	v_add_f32_e32 v195, v51, v195
	v_exp_f32_e32 v53, v53
	v_add_f32_e32 v195, v52, v195
	v_exp_f32_e32 v54, v54
	v_add_f32_e32 v195, v53, v195
	v_mfma_f32_32x32x16_bf16 v[64:79], v[152:155], v[104:107], v[64:79]
	v_exp_f32_e32 v55, v55
	v_add_f32_e32 v195, v54, v195
	v_exp_f32_e32 v56, v56
	v_add_f32_e32 v195, v55, v195
	v_exp_f32_e32 v57, v57
	v_add_f32_e32 v195, v56, v195
	s_waitcnt lgkmcnt(8)
	v_mfma_f32_32x32x16_bf16 v[80:95], v[164:167], v[104:107], v[80:95]
	v_exp_f32_e32 v58, v58
	v_add_f32_e32 v195, v57, v195
	v_exp_f32_e32 v59, v59
	v_add_f32_e32 v195, v58, v195
	v_exp_f32_e32 v60, v60
	v_add_f32_e32 v195, v59, v195
	s_waitcnt lgkmcnt(7)
	v_mfma_f32_32x32x16_bf16 v[64:79], v[156:159], v[108:111], v[64:79]
	v_exp_f32_e32 v61, v61
	v_add_f32_e32 v195, v60, v195
	v_exp_f32_e32 v62, v62
	v_add_f32_e32 v195, v61, v195
	v_exp_f32_e32 v63, v63
	v_add_f32_e32 v195, v62, v195
	v_add_f32_e32 v195, v63, v195
	s_waitcnt lgkmcnt(5)
	v_mfma_f32_32x32x16_bf16 v[80:95], v[176:179], v[108:111], v[80:95]
	v_exp_f32_e32 v32, v32
	v_exp_f32_e32 v33, v33
	v_exp_f32_e32 v34, v34
	v_add_f32_e32 v251, v32, v33
	v_cvt_pk_bf16_f32 v48, v48, v49
	v_exp_f32_e32 v35, v35
	v_mfma_f32_32x32x16_bf16 v[64:79], v[140:143], v[112:115], v[64:79]
	v_add_f32_e32 v251, v34, v251
	v_exp_f32_e32 v36, v36
	v_add_f32_e32 v251, v35, v251
	v_cvt_pk_bf16_f32 v49, v50, v51
	v_exp_f32_e32 v37, v37
	v_add_f32_e32 v251, v36, v251
	s_waitcnt lgkmcnt(4)
	v_mfma_f32_32x32x16_bf16 v[80:95], v[160:163], v[112:115], v[80:95]
	v_exp_f32_e32 v38, v38
	v_add_f32_e32 v251, v37, v251
	v_cvt_pk_bf16_f32 v50, v52, v53
	v_exp_f32_e32 v39, v39
	v_add_f32_e32 v251, v38, v251
	v_exp_f32_e32 v40, v40
	v_add_f32_e32 v251, v39, v251
	s_waitcnt lgkmcnt(3)
	v_mfma_f32_32x32x16_bf16 v[64:79], v[148:151], v[116:119], v[64:79]
	v_cvt_pk_bf16_f32 v51, v54, v55
	v_exp_f32_e32 v41, v41
	v_add_f32_e32 v251, v40, v251
	v_exp_f32_e32 v42, v42
	v_add_f32_e32 v251, v41, v251
	v_cvt_pk_bf16_f32 v52, v56, v57
	v_exp_f32_e32 v43, v43
	v_add_u32_e32 v196, v208, v184
	ds_read_b128 v[212:215], v196 offset:44544
	ds_read_b128 v[216:219], v196 offset:39936
	ds_read_b128 v[220:223], v196 offset:39968
	ds_read_b128 v[224:227], v196 offset:44576
	ds_read_b128 v[228:231], v196 offset:40000
	ds_read_b128 v[232:235], v196 offset:44608
	ds_read_b128 v[236:239], v196 offset:40032
	ds_read_b128 v[240:243], v196 offset:44640
	s_waitcnt lgkmcnt(9)
	v_mfma_f32_32x32x16_bf16 v[80:95], v[168:171], v[116:119], v[80:95]
	v_add_f32_e32 v251, v42, v251
	v_exp_f32_e32 v44, v44
	v_add_f32_e32 v251, v43, v251
	v_cvt_pk_bf16_f32 v53, v58, v59
	v_exp_f32_e32 v45, v45
	v_add_f32_e32 v251, v44, v251
	v_mfma_f32_32x32x16_bf16 v[64:79], v[136:139], v[120:123], v[64:79]
	v_exp_f32_e32 v46, v46
	v_add_f32_e32 v251, v45, v251
	v_cvt_pk_bf16_f32 v54, v60, v61
	v_exp_f32_e32 v47, v47
	v_add_f32_e32 v251, v46, v251
	v_add_f32_e32 v251, v47, v251
	v_cvt_pk_bf16_f32 v55, v62, v63
	v_cvt_pk_bf16_f32 v32, v32, v33
	s_waitcnt lgkmcnt(8)
	v_mfma_f32_32x32x16_bf16 v[80:95], v[144:147], v[120:123], v[80:95]
	v_cvt_pk_bf16_f32 v33, v34, v35
	v_cvt_pk_bf16_f32 v34, v36, v37
	v_cvt_pk_bf16_f32 v35, v38, v39
	v_cvt_pk_bf16_f32 v36, v40, v41
	v_cvt_pk_bf16_f32 v37, v42, v43
	v_cvt_pk_bf16_f32 v38, v44, v45
	v_cvt_pk_bf16_f32 v39, v46, v47
	v_add_f32_e32 v195, v195, v251
	v_add_f32_e32 v198, v198, v195
	s_waitcnt lgkmcnt(0)
	s_barrier

	v_add_u32_e32 v197, s6, v209
	v_mfma_f32_32x32x16_bf16 v[0:15], v[48:51], v[212:215], v[0:15]
	ds_read_b128 v[172:175], v197
	ds_read_b128 v[152:155], v197 offset:32
	v_mfma_f32_32x32x16_bf16 v[0:15], v[52:55], v[224:227], v[0:15]
	ds_read_b128 v[180:183], v197 offset:6656
	ds_read_b128 v[164:167], v197 offset:6688
	v_mfma_f32_32x32x16_bf16 v[0:15], v[32:35], v[232:235], v[0:15]
	ds_read_b128 v[156:159], v197 offset:64
	ds_read_b128 v[140:143], v197 offset:96
	v_mfma_f32_32x32x16_bf16 v[0:15], v[36:39], v[240:243], v[0:15]
	ds_read_b128 v[176:179], v197 offset:6720
	ds_read_b128 v[160:163], v197 offset:6752
	v_mfma_f32_32x32x16_bf16 v[16:31], v[48:51], v[216:219], v[16:31]
	ds_read_b128 v[148:151], v197 offset:128
	ds_read_b128 v[136:139], v197 offset:160
	v_mfma_f32_32x32x16_bf16 v[16:31], v[52:55], v[220:223], v[16:31]
	ds_read_b128 v[168:171], v197 offset:6784
	ds_read_b128 v[144:147], v197 offset:6816
	v_mfma_f32_32x32x16_bf16 v[16:31], v[32:35], v[228:231], v[16:31]
	s_add_i32 s4, s90, 1
	s_cmp_lg_u32 s90, 2
	s_cselect_b32 s68, s4, 0
	s_mul_i32 s6, s68, 0x3400
	s_add_i32 s7, s6, 0
	s_add_u32 s98, s98, 0x3000
	s_addc_u32 s99, s99, 0

	v_add_u32_e32 v253, s7, v96
	s_waitcnt vmcnt(1)
	ds_write_b128 v253, v[128:131]
	s_and_saveexec_b64 s[4:5], s[2:3]
	v_add_u32_e32 v253, s7, v185
	ds_write_b128 v253, v[124:127]
	s_or_b64 exec, exec, s[4:5]
	v_lshl_add_u64 v[200:201], s[100:101], 0, v[204:205]

	s_waitcnt vmcnt(0)
	ds_write2_b64 v211, v[132:133], v[134:135] offset0:128 offset1:130
	v_lshl_add_u64 v[128:129], s[98:99], 0, v[98:99]
	s_nop 0
	global_load_dwordx4 v[128:131], v[128:129], off

	s_and_saveexec_b64 s[4:5], s[2:3]
	s_cbranch_execz .Lat7B_L_h1
	v_lshl_add_u64 v[124:125], s[98:99], 0, v[202:203]
	s_nop 0
	global_load_dwordx4 v[124:127], v[124:125], off
.Lat7B_L_h1:
	s_or_b64 exec, exec, s[4:5]
	global_load_dwordx4 v[132:135], v[200:201], off offset:384

	s_sub_u32 s98, s98, 0x3000
	s_subb_u32 s99, s99, 0

	v_mfma_f32_32x32x16_bf16 v[16:31], v[36:39], v[236:239], v[16:31]
	s_waitcnt lgkmcnt(0)
	s_barrier
	s_waitcnt lgkmcnt(11)
	v_mfma_f32_32x32x16_bf16 v[48:63], v[172:175], v[100:103], 0
	v_exp_f32_e32 v64, v64
	v_exp_f32_e32 v65, v65
	v_exp_f32_e32 v66, v66
	v_add_f32_e32 v195, v64, v65
	v_exp_f32_e32 v67, v67
	s_waitcnt lgkmcnt(9)
	v_mfma_f32_32x32x16_bf16 v[32:47], v[180:183], v[100:103], 0
	v_add_f32_e32 v195, v66, v195
	v_exp_f32_e32 v68, v68
	v_add_f32_e32 v195, v67, v195
	v_exp_f32_e32 v69, v69
	v_add_f32_e32 v195, v68, v195
	v_exp_f32_e32 v70, v70
	v_add_f32_e32 v195, v69, v195
	v_mfma_f32_32x32x16_bf16 v[48:63], v[152:155], v[104:107], v[48:63]
	v_exp_f32_e32 v71, v71
	v_add_f32_e32 v195, v70, v195
	v_exp_f32_e32 v72, v72
	v_add_f32_e32 v195, v71, v195
	v_exp_f32_e32 v73, v73
	v_add_f32_e32 v195, v72, v195
	s_waitcnt lgkmcnt(8)
	v_mfma_f32_32x32x16_bf16 v[32:47], v[164:167], v[104:107], v[32:47]
	v_exp_f32_e32 v74, v74
	v_add_f32_e32 v195, v73, v195
	v_exp_f32_e32 v75, v75
	v_add_f32_e32 v195, v74, v195
	v_exp_f32_e32 v76, v76
	v_add_f32_e32 v195, v75, v195
	s_waitcnt lgkmcnt(7)
	v_mfma_f32_32x32x16_bf16 v[48:63], v[156:159], v[108:111], v[48:63]
	v_exp_f32_e32 v77, v77
	v_add_f32_e32 v195, v76, v195
	v_exp_f32_e32 v78, v78
	v_add_f32_e32 v195, v77, v195
	v_exp_f32_e32 v79, v79
	v_add_f32_e32 v195, v78, v195
	v_add_f32_e32 v195, v79, v195
	s_waitcnt lgkmcnt(5)
	v_mfma_f32_32x32x16_bf16 v[32:47], v[176:179], v[108:111], v[32:47]
	v_exp_f32_e32 v80, v80
	v_exp_f32_e32 v81, v81
	v_exp_f32_e32 v82, v82
	v_add_f32_e32 v251, v80, v81
	v_cvt_pk_bf16_f32 v64, v64, v65
	v_exp_f32_e32 v83, v83
	v_mfma_f32_32x32x16_bf16 v[48:63], v[140:143], v[112:115], v[48:63]
	v_add_f32_e32 v251, v82, v251
	v_exp_f32_e32 v84, v84
	v_add_f32_e32 v251, v83, v251
	v_cvt_pk_bf16_f32 v65, v66, v67
	v_exp_f32_e32 v85, v85
	v_add_f32_e32 v251, v84, v251
	s_waitcnt lgkmcnt(4)
	v_mfma_f32_32x32x16_bf16 v[32:47], v[160:163], v[112:115], v[32:47]
	v_exp_f32_e32 v86, v86
	v_add_f32_e32 v251, v85, v251
	v_cvt_pk_bf16_f32 v66, v68, v69
	v_exp_f32_e32 v87, v87
	v_add_f32_e32 v251, v86, v251
	v_exp_f32_e32 v88, v88
	v_add_f32_e32 v251, v87, v251
	s_waitcnt lgkmcnt(3)
	v_mfma_f32_32x32x16_bf16 v[48:63], v[148:151], v[116:119], v[48:63]
	v_cvt_pk_bf16_f32 v67, v70, v71
	v_exp_f32_e32 v89, v89
	v_add_f32_e32 v251, v88, v251
	v_exp_f32_e32 v90, v90
	v_add_f32_e32 v251, v89, v251
	v_cvt_pk_bf16_f32 v68, v72, v73
	v_exp_f32_e32 v91, v91
	v_add_u32_e32 v196, v208, v184
	ds_read_b128 v[212:215], v196 offset:53760
	ds_read_b128 v[216:219], v196 offset:49152
	ds_read_b128 v[220:223], v196 offset:49184
	ds_read_b128 v[224:227], v196 offset:53792
	ds_read_b128 v[228:231], v196 offset:49216
	ds_read_b128 v[232:235], v196 offset:53824
	ds_read_b128 v[236:239], v196 offset:49248
	ds_read_b128 v[240:243], v196 offset:53856
	s_waitcnt lgkmcnt(9)
	v_mfma_f32_32x32x16_bf16 v[32:47], v[168:171], v[116:119], v[32:47]
	v_add_f32_e32 v251, v90, v251
	v_exp_f32_e32 v92, v92
	v_add_f32_e32 v251, v91, v251
	v_cvt_pk_bf16_f32 v69, v74, v75
	v_exp_f32_e32 v93, v93
	v_add_f32_e32 v251, v92, v251
	v_mfma_f32_32x32x16_bf16 v[48:63], v[136:139], v[120:123], v[48:63]
	v_exp_f32_e32 v94, v94
	v_add_f32_e32 v251, v93, v251
	v_cvt_pk_bf16_f32 v70, v76, v77
	v_exp_f32_e32 v95, v95
	v_add_f32_e32 v251, v94, v251
	v_add_f32_e32 v251, v95, v251
	v_cvt_pk_bf16_f32 v71, v78, v79
	v_cvt_pk_bf16_f32 v80, v80, v81
	s_waitcnt lgkmcnt(8)
	v_mfma_f32_32x32x16_bf16 v[32:47], v[144:147], v[120:123], v[32:47]
	v_cvt_pk_bf16_f32 v81, v82, v83
	v_cvt_pk_bf16_f32 v82, v84, v85
	v_cvt_pk_bf16_f32 v83, v86, v87
	v_cvt_pk_bf16_f32 v84, v88, v89
	v_cvt_pk_bf16_f32 v85, v90, v91
	v_cvt_pk_bf16_f32 v86, v92, v93
	v_cvt_pk_bf16_f32 v87, v94, v95
	v_add_f32_e32 v195, v195, v251
	v_add_f32_e32 v198, v198, v195
	s_add_i32 s40, s40, 2
	s_waitcnt lgkmcnt(0)
	s_barrier

	v_add_u32_e32 v197, s6, v209
	v_mfma_f32_32x32x16_bf16 v[0:15], v[64:67], v[212:215], v[0:15]
	ds_read_b128 v[172:175], v197
	ds_read_b128 v[152:155], v197 offset:32
	v_mfma_f32_32x32x16_bf16 v[0:15], v[68:71], v[224:227], v[0:15]
	ds_read_b128 v[180:183], v197 offset:6656
	ds_read_b128 v[164:167], v197 offset:6688
	v_mfma_f32_32x32x16_bf16 v[0:15], v[80:83], v[232:235], v[0:15]
	ds_read_b128 v[156:159], v197 offset:64
	ds_read_b128 v[140:143], v197 offset:96
	v_mfma_f32_32x32x16_bf16 v[0:15], v[84:87], v[240:243], v[0:15]
	ds_read_b128 v[176:179], v197 offset:6720
	ds_read_b128 v[160:163], v197 offset:6752
	v_mfma_f32_32x32x16_bf16 v[16:31], v[64:67], v[216:219], v[16:31]
	ds_read_b128 v[148:151], v197 offset:128
	ds_read_b128 v[136:139], v197 offset:160
	v_mfma_f32_32x32x16_bf16 v[16:31], v[68:71], v[220:223], v[16:31]
	ds_read_b128 v[168:171], v197 offset:6784
	ds_read_b128 v[144:147], v197 offset:6816
	v_mfma_f32_32x32x16_bf16 v[16:31], v[80:83], v[228:231], v[16:31]
	s_add_i32 s4, s68, 1
	s_cmp_lg_u32 s68, 2
	s_cselect_b32 s90, s4, 0
	v_lshl_add_u64 v[98:99], v[98:99], 0, s[82:83]
	v_lshl_add_u64 v[202:203], v[202:203], 0, s[82:83]
	v_lshl_add_u64 v[204:205], v[204:205], 0, s[66:67]

	s_cmp_ge_u32 s40, s69
	s_cbranch_scc1 .Lst7B_Lskip

	s_mul_i32 s6, s90, 0x3400
	s_add_i32 s7, s6, 0

	v_add_u32_e32 v253, s7, v96
	s_waitcnt vmcnt(1)
	ds_write_b128 v253, v[128:131]
	s_and_saveexec_b64 s[4:5], s[2:3]
	v_add_u32_e32 v253, s7, v185
	ds_write_b128 v253, v[124:127]
	s_or_b64 exec, exec, s[4:5]
	v_lshl_add_u64 v[200:201], s[100:101], 0, v[204:205]

	v_add_u32_e32 v254, 0xc000, v210
	v_lshl_add_u64 v[128:129], s[98:99], 0, v[98:99]
	s_nop 0
	global_load_dwordx4 v[128:131], v[128:129], off
	s_waitcnt vmcnt(1)
	ds_write2_b64 v254, v[132:133], v[134:135] offset1:2

	s_and_saveexec_b64 s[4:5], s[2:3]
	s_cbranch_execz .Lat7B_L_h0
	v_lshl_add_u64 v[124:125], s[98:99], 0, v[202:203]
	s_nop 0
	global_load_dwordx4 v[124:127], v[124:125], off

.Lst7B_Lskip:
	v_mfma_f32_32x32x16_bf16 v[16:31], v[84:87], v[236:239], v[16:31]
	s_waitcnt lgkmcnt(0)
	s_barrier
	s_cmp_ge_u32 s40, s69
	s_cbranch_scc0 .Lst7B_Lloop
	s_branch .LBB0_1115

